# P1 sq/sk epilogue: the 8 per-row-group sums of squares reduced across lanes in one batch (2 waits) instead of 16 serial ds_bpermute round trips, on cvb
# speedup vs baseline: 1.0009x; 1.0009x over previous
;     __device__ __forceinline__ void operator()(const f32x4 (&acc)[2][2][4][2], const Unit& u, int wr, int wc, int fr, int fq) const {
;     ...
;             const int head = (u.pn & 3) * 4 + wc; const float* gp = (sec == 4 ? qg : kg) + head * 64 + 8 * fq;
;             float gn[2][8];
; #pragma unroll
;             for (int bj = 0; bj < 2; ++bj) { const f32x4 a = *(const f32x4*)(gp + 32 * bj), b = *(const f32x4*)(gp + 32 * bj + 4);
;                 gn[bj][0] = a[0]; gn[bj][1] = a[1]; gn[bj][2] = a[2]; gn[bj][3] = a[3]; gn[bj][4] = b[0]; gn[bj][5] = b[1]; gn[bj][6] = b[2]; gn[bj][7] = b[3]; }
;             const float sc = (sec == 4) ? 0.125f * 1.4426950408889634f : 1.0f;
; #pragma unroll
;             for (int ai = 0; ai < 2; ++ai)
; #pragma unroll
;                 for (int m = 0; m < 4; ++m) {
;                     float ss = 0.f;
; #pragma unroll
;                     for (int bj = 0; bj < 2; ++bj)
; #pragma unroll
;                         for (int n = 0; n < 2; ++n) { const f32x4 x = acc[ai][bj][m][n]; ss += (x[0] * x[0] + x[1] * x[1]) + (x[2] * x[2] + x[3] * x[3]); }
;                     ss += __shfl_xor(ss, 16); ss += __shfl_xor(ss, 32);
;                     const float rstd = __builtin_amdgcn_rsqf(ss * (1.0f / 64.0f) + 1e-6f) * sc;
.LBB0_128:
	s_and_b64 vcc, exec, s[0:1]
	s_cbranch_vccz .LBB0_127
	s_cmp_eq_u32 s49, 4
	s_cselect_b64 vcc, -1, 0
	s_and_b64 s[0:1], vcc, exec
	s_cselect_b32 s1, s63, s65
	s_cselect_b32 s0, s62, s64
	s_or_b32 s8, s8, s96
	s_lshl_b32 s20, s8, 2
	s_add_u32 s0, s0, s20
	s_addc_u32 s1, s1, 0
	v_lshlrev_b32_e32 v132, 2, v154
	global_load_dwordx4 v[136:139], v132, s[0:1] offset:16
	global_load_dwordx4 v[140:143], v132, s[0:1]
	global_load_dwordx4 v[128:131], v132, s[0:1] offset:144
	s_nop 0
	global_load_dwordx4 v[132:135], v132, s[0:1] offset:128
	v_xor_b32_e32 v246, 16, v184
	v_xor_b32_e32 v247, 32, v184
	v_lshlrev_b32_e32 v246, 2, v246
	v_lshlrev_b32_e32 v247, 2, v247
	v_pk_mul_f32 v[248:249], v[112:113], v[112:113]
	v_pk_mul_f32 v[250:251], v[114:115], v[114:115]
	v_pk_fma_f32 v[248:249], v[116:117], v[116:117], v[248:249]
	v_pk_fma_f32 v[250:251], v[118:119], v[118:119], v[250:251]
	v_pk_fma_f32 v[248:249], v[120:121], v[120:121], v[248:249]
	v_pk_fma_f32 v[250:251], v[122:123], v[122:123], v[250:251]
	v_pk_fma_f32 v[248:249], v[124:125], v[124:125], v[248:249]
	v_pk_fma_f32 v[250:251], v[126:127], v[126:127], v[250:251]
	s_nop 0
	v_pk_add_f32 v[248:249], v[248:249], v[250:251]
	s_nop 0
	v_add_f32_e32 v230, v248, v249
	v_pk_mul_f32 v[248:249], v[96:97], v[96:97]
	v_pk_mul_f32 v[250:251], v[98:99], v[98:99]
	v_pk_fma_f32 v[248:249], v[100:101], v[100:101], v[248:249]
	v_pk_fma_f32 v[250:251], v[102:103], v[102:103], v[250:251]
	v_pk_fma_f32 v[248:249], v[104:105], v[104:105], v[248:249]
	v_pk_fma_f32 v[250:251], v[106:107], v[106:107], v[250:251]
	v_pk_fma_f32 v[248:249], v[108:109], v[108:109], v[248:249]
	v_pk_fma_f32 v[250:251], v[110:111], v[110:111], v[250:251]
	s_nop 0
	v_pk_add_f32 v[248:249], v[248:249], v[250:251]
	s_nop 0
	v_add_f32_e32 v231, v248, v249
	v_pk_mul_f32 v[248:249], v[80:81], v[80:81]
	v_pk_mul_f32 v[250:251], v[82:83], v[82:83]
	v_pk_fma_f32 v[248:249], v[84:85], v[84:85], v[248:249]
	v_pk_fma_f32 v[250:251], v[86:87], v[86:87], v[250:251]
	v_pk_fma_f32 v[248:249], v[88:89], v[88:89], v[248:249]
	v_pk_fma_f32 v[250:251], v[90:91], v[90:91], v[250:251]
	v_pk_fma_f32 v[248:249], v[92:93], v[92:93], v[248:249]
	v_pk_fma_f32 v[250:251], v[94:95], v[94:95], v[250:251]
	s_nop 0
	v_pk_add_f32 v[248:249], v[248:249], v[250:251]
	s_nop 0
	v_add_f32_e32 v232, v248, v249
	v_pk_mul_f32 v[248:249], v[64:65], v[64:65]
	v_pk_mul_f32 v[250:251], v[66:67], v[66:67]
	v_pk_fma_f32 v[248:249], v[68:69], v[68:69], v[248:249]
	v_pk_fma_f32 v[250:251], v[70:71], v[70:71], v[250:251]
	v_pk_fma_f32 v[248:249], v[72:73], v[72:73], v[248:249]
	v_pk_fma_f32 v[250:251], v[74:75], v[74:75], v[250:251]
	v_pk_fma_f32 v[248:249], v[76:77], v[76:77], v[248:249]
	v_pk_fma_f32 v[250:251], v[78:79], v[78:79], v[250:251]
	s_nop 0
	v_pk_add_f32 v[248:249], v[248:249], v[250:251]
	s_nop 0
	v_add_f32_e32 v233, v248, v249
	v_pk_mul_f32 v[248:249], v[48:49], v[48:49]
	v_pk_mul_f32 v[250:251], v[50:51], v[50:51]
	v_pk_fma_f32 v[248:249], v[52:53], v[52:53], v[248:249]
	v_pk_fma_f32 v[250:251], v[54:55], v[54:55], v[250:251]
	v_pk_fma_f32 v[248:249], v[56:57], v[56:57], v[248:249]
	v_pk_fma_f32 v[250:251], v[58:59], v[58:59], v[250:251]
	v_pk_fma_f32 v[248:249], v[60:61], v[60:61], v[248:249]
	v_pk_fma_f32 v[250:251], v[62:63], v[62:63], v[250:251]
	s_nop 0
	v_pk_add_f32 v[248:249], v[248:249], v[250:251]
	s_nop 0
	v_add_f32_e32 v234, v248, v249
	v_pk_mul_f32 v[248:249], v[32:33], v[32:33]
	v_pk_mul_f32 v[250:251], v[34:35], v[34:35]
	v_pk_fma_f32 v[248:249], v[36:37], v[36:37], v[248:249]
	v_pk_fma_f32 v[250:251], v[38:39], v[38:39], v[250:251]
	v_pk_fma_f32 v[248:249], v[40:41], v[40:41], v[248:249]
	v_pk_fma_f32 v[250:251], v[42:43], v[42:43], v[250:251]
	v_pk_fma_f32 v[248:249], v[44:45], v[44:45], v[248:249]
	v_pk_fma_f32 v[250:251], v[46:47], v[46:47], v[250:251]
	s_nop 0
	v_pk_add_f32 v[248:249], v[248:249], v[250:251]
	s_nop 0
	v_add_f32_e32 v235, v248, v249
	v_pk_mul_f32 v[248:249], v[16:17], v[16:17]
	v_pk_mul_f32 v[250:251], v[18:19], v[18:19]
	v_pk_fma_f32 v[248:249], v[20:21], v[20:21], v[248:249]
	v_pk_fma_f32 v[250:251], v[22:23], v[22:23], v[250:251]
	v_pk_fma_f32 v[248:249], v[24:25], v[24:25], v[248:249]
	v_pk_fma_f32 v[250:251], v[26:27], v[26:27], v[250:251]
	v_pk_fma_f32 v[248:249], v[28:29], v[28:29], v[248:249]
	v_pk_fma_f32 v[250:251], v[30:31], v[30:31], v[250:251]
	s_nop 0
	v_pk_add_f32 v[248:249], v[248:249], v[250:251]
	s_nop 0
	v_add_f32_e32 v236, v248, v249
	v_pk_mul_f32 v[248:249], v[0:1], v[0:1]
	v_pk_mul_f32 v[250:251], v[2:3], v[2:3]
	v_pk_fma_f32 v[248:249], v[4:5], v[4:5], v[248:249]
	v_pk_fma_f32 v[250:251], v[6:7], v[6:7], v[250:251]
	v_pk_fma_f32 v[248:249], v[8:9], v[8:9], v[248:249]
	v_pk_fma_f32 v[250:251], v[10:11], v[10:11], v[250:251]
	v_pk_fma_f32 v[248:249], v[12:13], v[12:13], v[248:249]
	v_pk_fma_f32 v[250:251], v[14:15], v[14:15], v[250:251]
	s_nop 0
	v_pk_add_f32 v[248:249], v[248:249], v[250:251]
	s_nop 0
	v_add_f32_e32 v237, v248, v249
	ds_bpermute_b32 v238, v246, v230
	ds_bpermute_b32 v239, v246, v231
	ds_bpermute_b32 v240, v246, v232
	ds_bpermute_b32 v241, v246, v233
	ds_bpermute_b32 v242, v246, v234
	ds_bpermute_b32 v243, v246, v235
	ds_bpermute_b32 v244, v246, v236
	ds_bpermute_b32 v245, v246, v237
	s_waitcnt lgkmcnt(0)
	v_add_f32_e32 v230, v230, v238
	v_add_f32_e32 v231, v231, v239
	v_add_f32_e32 v232, v232, v240
	v_add_f32_e32 v233, v233, v241
	v_add_f32_e32 v234, v234, v242
	v_add_f32_e32 v235, v235, v243
	v_add_f32_e32 v236, v236, v244
	v_add_f32_e32 v237, v237, v245
	ds_bpermute_b32 v238, v247, v230
	ds_bpermute_b32 v239, v247, v231
	ds_bpermute_b32 v240, v247, v232
	ds_bpermute_b32 v241, v247, v233
	ds_bpermute_b32 v242, v247, v234
	ds_bpermute_b32 v243, v247, v235
	ds_bpermute_b32 v244, v247, v236
	ds_bpermute_b32 v245, v247, v237
	s_waitcnt lgkmcnt(0)
; __device__ __forceinline__ u32x4 pack8_bf16(const float (&o)[8]) { u32x4 w; w.x = cvt_pk_bf16(o[0], o[1]); w.y = cvt_pk_bf16(o[2], o[3]); w.z = cvt_pk_bf16(o[4], o[5]); w.w = cvt_pk_bf16(o[6], o[7]); return w; }
;     __device__ __forceinline__ void operator()(const f32x4 (&acc)[2][2][4][2], const Unit& u, int wr, int wc, int fr, int fq) const {
;     ...
;                         for (int n = 0; n < 2; ++n) { const f32x4 x = acc[ai][bj][m][n]; ss += (x[0] * x[0] + x[1] * x[1]) + (x[2] * x[2] + x[3] * x[3]); }
;                     ss += __shfl_xor(ss, 16); ss += __shfl_xor(ss, 32);
;                     const float rstd = __builtin_amdgcn_rsqf(ss * (1.0f / 64.0f) + 1e-6f) * sc;
;                     const size_t row = (size_t)(row0 + ai * HALF + m * 16);
; #pragma unroll
;                     for (int bj = 0; bj < 2; ++bj) { float o[8];
; #pragma unroll
;                         for (int k = 0; k < 8; ++k) o[k] = acc[ai][bj][m][k >> 2][k & 3] * rstd * gn[bj][k];
;                         bf16_t* dst = (sec == 4) ? (QS + row * 2048 + 1024 + head * 64 + 32 * bj + 8 * fq) : (SK + row * 1024 + head * 64 + 32 * bj + 8 * fq);
;                         *(u32x4*)dst = pack8_bf16(o); }
;                 }
	v_add_f32_e32 v230, v230, v238
	v_add_f32_e32 v231, v231, v239
	v_add_f32_e32 v232, v232, v240
	v_add_f32_e32 v233, v233, v241
	v_add_f32_e32 v234, v234, v242
	v_add_f32_e32 v235, v235, v243
	v_add_f32_e32 v236, v236, v244
	v_add_f32_e32 v237, v237, v245
	v_and_b32_e32 v167, 64, v184
	v_xor_b32_e32 v152, 16, v184
	v_add_u32_e32 v167, 64, v167
	v_cmp_lt_i32_e64 s[0:1], v152, v167
	v_pk_mul_f32 v[170:171], v[126:127], v[126:127]
	v_pk_mul_f32 v[172:173], v[124:125], v[124:125]
	v_cndmask_b32_e64 v152, v184, v152, s[0:1]
	v_pk_mov_b32 v[186:187], v[172:173], v[170:171] op_sel:[1,0]
	v_mov_b32_e32 v173, v171
	v_lshlrev_b32_e32 v174, 2, v152
	v_xor_b32_e32 v152, 32, v184
	v_pk_add_f32 v[170:171], v[186:187], v[172:173]
	v_pk_mul_f32 v[172:173], v[122:123], v[122:123]
	v_pk_mul_f32 v[186:187], v[120:121], v[120:121]
	v_cmp_lt_i32_e64 s[0:1], v152, v167
	v_pk_mov_b32 v[190:191], v[186:187], v[172:173] op_sel:[1,0]
	v_mov_b32_e32 v187, v173
	v_cndmask_b32_e64 v152, v184, v152, s[0:1]
	v_pk_add_f32 v[172:173], v[190:191], v[186:187]
	v_lshlrev_b32_e32 v175, 2, v152
	v_mul_f32_e32 v152, v112, v112
	v_mul_f32_e32 v167, v113, v113
	v_pk_add_f32 v[170:171], v[170:171], v[170:171] op_sel:[0,1] op_sel_hi:[1,0]
	v_pk_add_f32 v[172:173], v[172:173], v[172:173] op_sel:[0,1] op_sel_hi:[1,0]
	v_mov_b32_e32 v171, v152
	v_mov_b32_e32 v173, v167
	v_mul_f32_e32 v152, v117, v117
	v_pk_add_f32 v[170:171], v[170:171], v[172:173]
	v_pk_fma_f32 v[172:173], v[116:117], v[116:117], v[152:153] op_sel_hi:[1,1,0]
	v_mul_f32_e32 v152, v119, v119
	v_mul_f32_e32 v168, v114, v114
	v_mul_f32_e32 v185, v115, v115
	v_pk_fma_f32 v[186:187], v[118:119], v[118:119], v[152:153] op_sel_hi:[1,1,0]
	v_mov_b32_e32 v173, v168
	v_mov_b32_e32 v187, v185
	v_pk_add_f32 v[172:173], v[172:173], v[186:187]
	v_cndmask_b32_e32 v169, 1.0, v183, vcc
	v_pk_add_f32 v[170:171], v[170:171], v[172:173]
	s_lshl_b32 s8, s8, 1
	v_add_f32_e32 v152, v170, v171
	s_and_b64 s[0:1], vcc, exec
	s_cselect_b32 s0, 0x840, 64
	s_mov_b32 s1, s9
	v_mov_b32_e32 v152, v230
	v_fmamk_f32 v152, v152, 0x3c800000, v182
	v_rsq_f32_e32 v152, v152
	v_ashrrev_i32_e32 v167, 31, v166
	v_lshlrev_b64 v[190:191], 12, v[166:167]
	v_lshlrev_b64 v[186:187], 11, v[166:167]
	v_mul_f32_e32 v168, v169, v152
	v_pk_mul_f32 v[120:121], v[120:121], v[168:169] op_sel_hi:[1,0]
	v_pk_mul_f32 v[124:125], v[124:125], v[168:169] op_sel_hi:[1,0]
	v_pk_mul_f32 v[126:127], v[126:127], v[168:169] op_sel_hi:[1,0]
	v_lshlrev_b32_e32 v152, 1, v154
	v_pk_mul_f32 v[112:113], v[112:113], v[168:169] op_sel_hi:[1,0]
	v_pk_mul_f32 v[116:117], v[116:117], v[168:169] op_sel_hi:[1,0]
	v_pk_mul_f32 v[118:119], v[118:119], v[168:169] op_sel_hi:[1,0]
	s_waitcnt vmcnt(0)
	v_pk_mul_f32 v[170:171], v[136:137], v[120:121]
	v_pk_mul_f32 v[120:121], v[122:123], v[168:169] op_sel_hi:[1,0]
	v_lshl_add_u64 v[122:123], s[18:19], 0, v[186:187]
	v_pk_mul_f32 v[172:173], v[138:139], v[120:121]
	v_lshl_add_u64 v[120:121], s[14:15], 0, v[190:191]
	v_lshl_add_u64 v[190:191], v[120:121], 0, s[46:47]
	v_cndmask_b32_e32 v187, v123, v191, vcc
	v_cndmask_b32_e32 v186, v122, v190, vcc
	v_pk_mul_f32 v[124:125], v[140:141], v[124:125]
	v_pk_mul_f32 v[126:127], v[142:143], v[126:127]
	v_lshl_add_u64 v[186:187], v[186:187], 0, s[8:9]
	v_lshl_add_u64 v[186:187], v[186:187], 0, v[152:153]
	v_cvt_pk_bf16_f32 v124, v124, v125
	v_cvt_pk_bf16_f32 v125, v126, v127
	v_cvt_pk_bf16_f32 v126, v170, v171
	v_cvt_pk_bf16_f32 v127, v172, v173
	global_store_dwordx4 v[186:187], v[124:127], off
	v_pk_mul_f32 v[116:117], v[132:133], v[116:117]
	v_pk_mul_f32 v[118:119], v[134:135], v[118:119]
	v_pk_mul_f32 v[124:125], v[128:129], v[112:113]
	v_pk_mul_f32 v[112:113], v[114:115], v[168:169] op_sel_hi:[1,0]
	v_cvt_pk_bf16_f32 v114, v124, v125
	v_pk_mul_f32 v[126:127], v[130:131], v[112:113]
	v_cndmask_b32_e32 v113, v123, v121, vcc
	v_cndmask_b32_e32 v112, v122, v120, vcc
	v_lshl_add_u64 v[112:113], v[112:113], 0, s[8:9]
	v_lshl_add_u64 v[112:113], v[112:113], 0, s[0:1]
	v_lshl_add_u64 v[120:121], v[112:113], 0, v[152:153]
	v_cvt_pk_bf16_f32 v112, v116, v117
	v_cvt_pk_bf16_f32 v113, v118, v119
	v_cvt_pk_bf16_f32 v115, v126, v127
	global_store_dwordx4 v[120:121], v[112:115], off
	s_nop 1
	v_pk_mul_f32 v[112:113], v[110:111], v[110:111]
	v_pk_mul_f32 v[114:115], v[108:109], v[108:109]
	s_nop 0
	v_pk_mov_b32 v[116:117], v[114:115], v[112:113] op_sel:[1,0]
	v_mov_b32_e32 v115, v113
	v_pk_add_f32 v[112:113], v[116:117], v[114:115]
	v_pk_mul_f32 v[114:115], v[106:107], v[106:107]
	v_pk_mul_f32 v[116:117], v[104:105], v[104:105]
	v_pk_add_f32 v[112:113], v[112:113], v[112:113] op_sel:[0,1] op_sel_hi:[1,0]
	v_pk_mov_b32 v[118:119], v[116:117], v[114:115] op_sel:[1,0]
	v_mov_b32_e32 v117, v115
	v_pk_add_f32 v[114:115], v[118:119], v[116:117]
	v_mul_f32_e32 v116, v96, v96
	v_mul_f32_e32 v117, v97, v97
	v_pk_add_f32 v[114:115], v[114:115], v[114:115] op_sel:[0,1] op_sel_hi:[1,0]
	v_mov_b32_e32 v113, v116
	v_mov_b32_e32 v115, v117
	v_pk_add_f32 v[112:113], v[112:113], v[114:115]
	v_mul_f32_e32 v114, v101, v101
	v_mul_f32_e32 v116, v103, v103
	v_mul_f32_e32 v118, v98, v98
	v_mul_f32_e32 v119, v99, v99
	v_pk_fma_f32 v[114:115], v[100:101], v[100:101], v[114:115] op_sel_hi:[1,1,0]
	v_pk_fma_f32 v[116:117], v[102:103], v[102:103], v[116:117] op_sel_hi:[1,1,0]
	v_mov_b32_e32 v115, v118
	v_mov_b32_e32 v117, v119
	v_pk_add_f32 v[114:115], v[114:115], v[116:117]
	s_nop 0
	v_pk_add_f32 v[112:113], v[112:113], v[114:115]
	v_or_b32_e32 v114, 16, v166
	v_add_f32_e32 v112, v112, v113
	v_ashrrev_i32_e32 v115, 31, v114
	v_lshlrev_b64 v[116:117], 11, v[114:115]
	v_lshlrev_b64 v[114:115], 12, v[114:115]
	v_lshl_add_u64 v[114:115], s[14:15], 0, v[114:115]
; __device__ __forceinline__ u32x4 pack8_bf16(const float (&o)[8]) { u32x4 w; w.x = cvt_pk_bf16(o[0], o[1]); w.y = cvt_pk_bf16(o[2], o[3]); w.z = cvt_pk_bf16(o[4], o[5]); w.w = cvt_pk_bf16(o[6], o[7]); return w; }
;     __device__ __forceinline__ void operator()(const f32x4 (&acc)[2][2][4][2], const Unit& u, int wr, int wc, int fr, int fq) const {
;     ...
;                         for (int n = 0; n < 2; ++n) { const f32x4 x = acc[ai][bj][m][n]; ss += (x[0] * x[0] + x[1] * x[1]) + (x[2] * x[2] + x[3] * x[3]); }
;                     ss += __shfl_xor(ss, 16); ss += __shfl_xor(ss, 32);
;                     const float rstd = __builtin_amdgcn_rsqf(ss * (1.0f / 64.0f) + 1e-6f) * sc;
;                     const size_t row = (size_t)(row0 + ai * HALF + m * 16);
; #pragma unroll
;                     for (int bj = 0; bj < 2; ++bj) { float o[8];
; #pragma unroll
;                         for (int k = 0; k < 8; ++k) o[k] = acc[ai][bj][m][k >> 2][k & 3] * rstd * gn[bj][k];
;                         bf16_t* dst = (sec == 4) ? (QS + row * 2048 + 1024 + head * 64 + 32 * bj + 8 * fq) : (SK + row * 1024 + head * 64 + 32 * bj + 8 * fq);
;                         *(u32x4*)dst = pack8_bf16(o); }
;                 }
	v_lshl_add_u64 v[116:117], s[18:19], 0, v[116:117]
	v_mov_b32_e32 v112, v231
	v_fmamk_f32 v112, v112, 0x3c800000, v182
	v_rsq_f32_e32 v112, v112
	s_nop 0
	v_mul_f32_e32 v112, v169, v112
	v_pk_mul_f32 v[104:105], v[104:105], v[112:113] op_sel_hi:[1,0]
	v_pk_mul_f32 v[108:109], v[108:109], v[112:113] op_sel_hi:[1,0]
	v_pk_mul_f32 v[118:119], v[136:137], v[104:105]
	v_pk_mul_f32 v[104:105], v[106:107], v[112:113] op_sel_hi:[1,0]
	v_pk_mul_f32 v[110:111], v[110:111], v[112:113] op_sel_hi:[1,0]
	v_pk_mul_f32 v[120:121], v[138:139], v[104:105]
	v_lshl_add_u64 v[104:105], v[114:115], 0, s[46:47]
	v_cndmask_b32_e32 v105, v117, v105, vcc
	v_cndmask_b32_e32 v104, v116, v104, vcc
	v_pk_mul_f32 v[108:109], v[140:141], v[108:109]
	v_pk_mul_f32 v[110:111], v[142:143], v[110:111]
	v_lshl_add_u64 v[104:105], v[104:105], 0, s[8:9]
	v_lshl_add_u64 v[122:123], v[104:105], 0, v[152:153]
	v_cvt_pk_bf16_f32 v104, v108, v109
	v_cvt_pk_bf16_f32 v105, v110, v111
	v_cvt_pk_bf16_f32 v106, v118, v119
	v_cvt_pk_bf16_f32 v107, v120, v121
	v_pk_mul_f32 v[96:97], v[96:97], v[112:113] op_sel_hi:[1,0]
	global_store_dwordx4 v[122:123], v[104:107], off
	v_pk_mul_f32 v[100:101], v[100:101], v[112:113] op_sel_hi:[1,0]
	v_pk_mul_f32 v[102:103], v[102:103], v[112:113] op_sel_hi:[1,0]
	v_pk_mul_f32 v[104:105], v[128:129], v[96:97]
	v_pk_mul_f32 v[96:97], v[98:99], v[112:113] op_sel_hi:[1,0]
	v_pk_mul_f32 v[100:101], v[132:133], v[100:101]
	v_pk_mul_f32 v[106:107], v[130:131], v[96:97]
	v_cndmask_b32_e32 v97, v117, v115, vcc
	v_cndmask_b32_e32 v96, v116, v114, vcc
	v_lshl_add_u64 v[96:97], v[96:97], 0, s[8:9]
	v_pk_mul_f32 v[102:103], v[134:135], v[102:103]
	v_lshl_add_u64 v[96:97], v[96:97], 0, s[0:1]
	v_lshl_add_u64 v[108:109], v[96:97], 0, v[152:153]
	v_cvt_pk_bf16_f32 v96, v100, v101
	v_cvt_pk_bf16_f32 v97, v102, v103
	v_cvt_pk_bf16_f32 v98, v104, v105
	v_cvt_pk_bf16_f32 v99, v106, v107
	global_store_dwordx4 v[108:109], v[96:99], off
	s_nop 1
	v_pk_mul_f32 v[96:97], v[94:95], v[94:95]
	v_pk_mul_f32 v[98:99], v[92:93], v[92:93]
	s_nop 0
	v_pk_mov_b32 v[100:101], v[98:99], v[96:97] op_sel:[1,0]
	v_mov_b32_e32 v99, v97
	v_pk_add_f32 v[96:97], v[100:101], v[98:99]
	v_pk_mul_f32 v[98:99], v[90:91], v[90:91]
	v_pk_mul_f32 v[100:101], v[88:89], v[88:89]
	v_pk_add_f32 v[96:97], v[96:97], v[96:97] op_sel:[0,1] op_sel_hi:[1,0]
	v_pk_mov_b32 v[102:103], v[100:101], v[98:99] op_sel:[1,0]
	v_mov_b32_e32 v101, v99
	v_pk_add_f32 v[98:99], v[102:103], v[100:101]
	v_mul_f32_e32 v100, v80, v80
	v_mul_f32_e32 v101, v81, v81
	v_pk_add_f32 v[98:99], v[98:99], v[98:99] op_sel:[0,1] op_sel_hi:[1,0]
	v_mov_b32_e32 v97, v100
	v_mov_b32_e32 v99, v101
	v_pk_add_f32 v[96:97], v[96:97], v[98:99]
	v_mul_f32_e32 v98, v85, v85
	v_mul_f32_e32 v100, v87, v87
	v_mul_f32_e32 v102, v82, v82
	v_mul_f32_e32 v103, v83, v83
	v_pk_fma_f32 v[98:99], v[84:85], v[84:85], v[98:99] op_sel_hi:[1,1,0]
	v_pk_fma_f32 v[100:101], v[86:87], v[86:87], v[100:101] op_sel_hi:[1,1,0]
	v_mov_b32_e32 v99, v102
	v_mov_b32_e32 v101, v103
	v_pk_add_f32 v[98:99], v[98:99], v[100:101]
	s_nop 0
	v_pk_add_f32 v[96:97], v[96:97], v[98:99]
	v_or_b32_e32 v98, 32, v166
	v_add_f32_e32 v96, v96, v97
	v_ashrrev_i32_e32 v99, 31, v98
	v_lshlrev_b64 v[100:101], 11, v[98:99]
	v_lshlrev_b64 v[98:99], 12, v[98:99]
	v_lshl_add_u64 v[98:99], s[14:15], 0, v[98:99]
	v_lshl_add_u64 v[100:101], s[18:19], 0, v[100:101]
	v_mov_b32_e32 v96, v232
	v_fmamk_f32 v96, v96, 0x3c800000, v182
	v_rsq_f32_e32 v96, v96
	s_nop 0
	v_mul_f32_e32 v96, v169, v96
	v_pk_mul_f32 v[88:89], v[88:89], v[96:97] op_sel_hi:[1,0]
	v_pk_mul_f32 v[92:93], v[92:93], v[96:97] op_sel_hi:[1,0]
	v_pk_mul_f32 v[102:103], v[136:137], v[88:89]
	v_pk_mul_f32 v[88:89], v[90:91], v[96:97] op_sel_hi:[1,0]
	v_pk_mul_f32 v[94:95], v[94:95], v[96:97] op_sel_hi:[1,0]
	v_pk_mul_f32 v[104:105], v[138:139], v[88:89]
	v_lshl_add_u64 v[88:89], v[98:99], 0, s[46:47]
	v_cndmask_b32_e32 v89, v101, v89, vcc
	v_cndmask_b32_e32 v88, v100, v88, vcc
	v_pk_mul_f32 v[92:93], v[140:141], v[92:93]
	v_pk_mul_f32 v[94:95], v[142:143], v[94:95]
	v_lshl_add_u64 v[88:89], v[88:89], 0, s[8:9]
	v_lshl_add_u64 v[106:107], v[88:89], 0, v[152:153]
	v_cvt_pk_bf16_f32 v88, v92, v93
	v_cvt_pk_bf16_f32 v89, v94, v95
	v_cvt_pk_bf16_f32 v90, v102, v103
	v_cvt_pk_bf16_f32 v91, v104, v105
	v_pk_mul_f32 v[80:81], v[80:81], v[96:97] op_sel_hi:[1,0]
	global_store_dwordx4 v[106:107], v[88:91], off
	v_pk_mul_f32 v[84:85], v[84:85], v[96:97] op_sel_hi:[1,0]
	v_pk_mul_f32 v[86:87], v[86:87], v[96:97] op_sel_hi:[1,0]
	v_pk_mul_f32 v[88:89], v[128:129], v[80:81]
	v_pk_mul_f32 v[80:81], v[82:83], v[96:97] op_sel_hi:[1,0]
	v_pk_mul_f32 v[84:85], v[132:133], v[84:85]
	v_pk_mul_f32 v[90:91], v[130:131], v[80:81]
	v_cndmask_b32_e32 v81, v101, v99, vcc
	v_cndmask_b32_e32 v80, v100, v98, vcc
	v_lshl_add_u64 v[80:81], v[80:81], 0, s[8:9]
	v_pk_mul_f32 v[86:87], v[134:135], v[86:87]
	v_lshl_add_u64 v[80:81], v[80:81], 0, s[0:1]
	v_lshl_add_u64 v[92:93], v[80:81], 0, v[152:153]
	v_cvt_pk_bf16_f32 v80, v84, v85
	v_cvt_pk_bf16_f32 v81, v86, v87
	v_cvt_pk_bf16_f32 v82, v88, v89
	v_cvt_pk_bf16_f32 v83, v90, v91
	global_store_dwordx4 v[92:93], v[80:83], off
	s_nop 1
	v_pk_mul_f32 v[80:81], v[78:79], v[78:79]
	v_pk_mul_f32 v[82:83], v[76:77], v[76:77]
	s_nop 0
	v_pk_mov_b32 v[84:85], v[82:83], v[80:81] op_sel:[1,0]
	v_mov_b32_e32 v83, v81
	v_pk_add_f32 v[80:81], v[84:85], v[82:83]
	v_pk_mul_f32 v[82:83], v[74:75], v[74:75]
	v_pk_mul_f32 v[84:85], v[72:73], v[72:73]
	v_pk_add_f32 v[80:81], v[80:81], v[80:81] op_sel:[0,1] op_sel_hi:[1,0]
	v_pk_mov_b32 v[86:87], v[84:85], v[82:83] op_sel:[1,0]
	v_mov_b32_e32 v85, v83
	v_pk_add_f32 v[82:83], v[86:87], v[84:85]
; __device__ __forceinline__ u32x4 pack8_bf16(const float (&o)[8]) { u32x4 w; w.x = cvt_pk_bf16(o[0], o[1]); w.y = cvt_pk_bf16(o[2], o[3]); w.z = cvt_pk_bf16(o[4], o[5]); w.w = cvt_pk_bf16(o[6], o[7]); return w; }
;     __device__ __forceinline__ void operator()(const f32x4 (&acc)[2][2][4][2], const Unit& u, int wr, int wc, int fr, int fq) const {
;     ...
;                         for (int n = 0; n < 2; ++n) { const f32x4 x = acc[ai][bj][m][n]; ss += (x[0] * x[0] + x[1] * x[1]) + (x[2] * x[2] + x[3] * x[3]); }
;                     ss += __shfl_xor(ss, 16); ss += __shfl_xor(ss, 32);
;                     const float rstd = __builtin_amdgcn_rsqf(ss * (1.0f / 64.0f) + 1e-6f) * sc;
;                     const size_t row = (size_t)(row0 + ai * HALF + m * 16);
; #pragma unroll
;                     for (int bj = 0; bj < 2; ++bj) { float o[8];
; #pragma unroll
;                         for (int k = 0; k < 8; ++k) o[k] = acc[ai][bj][m][k >> 2][k & 3] * rstd * gn[bj][k];
;                         bf16_t* dst = (sec == 4) ? (QS + row * 2048 + 1024 + head * 64 + 32 * bj + 8 * fq) : (SK + row * 1024 + head * 64 + 32 * bj + 8 * fq);
;                         *(u32x4*)dst = pack8_bf16(o); }
;                 }
	v_mul_f32_e32 v84, v64, v64
	v_mul_f32_e32 v85, v65, v65
	v_pk_add_f32 v[82:83], v[82:83], v[82:83] op_sel:[0,1] op_sel_hi:[1,0]
	v_mov_b32_e32 v81, v84
	v_mov_b32_e32 v83, v85
	v_pk_add_f32 v[80:81], v[80:81], v[82:83]
	v_mul_f32_e32 v82, v69, v69
	v_mul_f32_e32 v84, v71, v71
	v_mul_f32_e32 v86, v66, v66
	v_mul_f32_e32 v87, v67, v67
	v_pk_fma_f32 v[82:83], v[68:69], v[68:69], v[82:83] op_sel_hi:[1,1,0]
	v_pk_fma_f32 v[84:85], v[70:71], v[70:71], v[84:85] op_sel_hi:[1,1,0]
	v_mov_b32_e32 v83, v86
	v_mov_b32_e32 v85, v87
	v_pk_add_f32 v[82:83], v[82:83], v[84:85]
	s_nop 0
	v_pk_add_f32 v[80:81], v[80:81], v[82:83]
	v_or_b32_e32 v82, 48, v166
	v_add_f32_e32 v80, v80, v81
	v_ashrrev_i32_e32 v83, 31, v82
	v_lshlrev_b64 v[84:85], 11, v[82:83]
	v_lshlrev_b64 v[82:83], 12, v[82:83]
	v_lshl_add_u64 v[82:83], s[14:15], 0, v[82:83]
	v_lshl_add_u64 v[84:85], s[18:19], 0, v[84:85]
	v_mov_b32_e32 v80, v233
	v_fmamk_f32 v80, v80, 0x3c800000, v182
	v_rsq_f32_e32 v80, v80
	s_nop 0
	v_mul_f32_e32 v80, v169, v80
	v_pk_mul_f32 v[72:73], v[72:73], v[80:81] op_sel_hi:[1,0]
	v_pk_mul_f32 v[76:77], v[76:77], v[80:81] op_sel_hi:[1,0]
	v_pk_mul_f32 v[86:87], v[136:137], v[72:73]
	v_pk_mul_f32 v[72:73], v[74:75], v[80:81] op_sel_hi:[1,0]
	v_pk_mul_f32 v[78:79], v[78:79], v[80:81] op_sel_hi:[1,0]
	v_pk_mul_f32 v[88:89], v[138:139], v[72:73]
	v_lshl_add_u64 v[72:73], v[82:83], 0, s[46:47]
	v_cndmask_b32_e32 v73, v85, v73, vcc
	v_cndmask_b32_e32 v72, v84, v72, vcc
	v_pk_mul_f32 v[76:77], v[140:141], v[76:77]
	v_pk_mul_f32 v[78:79], v[142:143], v[78:79]
	v_lshl_add_u64 v[72:73], v[72:73], 0, s[8:9]
	v_lshl_add_u64 v[90:91], v[72:73], 0, v[152:153]
	v_cvt_pk_bf16_f32 v72, v76, v77
	v_cvt_pk_bf16_f32 v73, v78, v79
	v_cvt_pk_bf16_f32 v74, v86, v87
	v_cvt_pk_bf16_f32 v75, v88, v89
	v_pk_mul_f32 v[64:65], v[64:65], v[80:81] op_sel_hi:[1,0]
	global_store_dwordx4 v[90:91], v[72:75], off
	v_pk_mul_f32 v[68:69], v[68:69], v[80:81] op_sel_hi:[1,0]
	v_pk_mul_f32 v[70:71], v[70:71], v[80:81] op_sel_hi:[1,0]
	v_pk_mul_f32 v[72:73], v[128:129], v[64:65]
	v_pk_mul_f32 v[64:65], v[66:67], v[80:81] op_sel_hi:[1,0]
	v_pk_mul_f32 v[68:69], v[132:133], v[68:69]
	v_pk_mul_f32 v[74:75], v[130:131], v[64:65]
	v_cndmask_b32_e32 v65, v85, v83, vcc
	v_cndmask_b32_e32 v64, v84, v82, vcc
	v_lshl_add_u64 v[64:65], v[64:65], 0, s[8:9]
	v_pk_mul_f32 v[70:71], v[134:135], v[70:71]
	v_lshl_add_u64 v[64:65], v[64:65], 0, s[0:1]
	v_lshl_add_u64 v[76:77], v[64:65], 0, v[152:153]
	v_cvt_pk_bf16_f32 v64, v68, v69
	v_cvt_pk_bf16_f32 v65, v70, v71
	v_cvt_pk_bf16_f32 v66, v72, v73
	v_cvt_pk_bf16_f32 v67, v74, v75
	global_store_dwordx4 v[76:77], v[64:67], off
	v_pk_mul_f32 v[68:69], v[60:61], v[60:61]
	s_nop 0
	v_pk_mul_f32 v[66:67], v[62:63], v[62:63]
	v_mul_f32_e32 v65, v48, v48
	v_pk_mov_b32 v[70:71], v[68:69], v[66:67] op_sel:[1,0]
	v_mov_b32_e32 v69, v67
	v_pk_add_f32 v[66:67], v[70:71], v[68:69]
	v_pk_mul_f32 v[68:69], v[58:59], v[58:59]
	v_pk_mul_f32 v[70:71], v[56:57], v[56:57]
	v_pk_add_f32 v[66:67], v[66:67], v[66:67] op_sel:[0,1] op_sel_hi:[1,0]
	v_pk_mov_b32 v[72:73], v[70:71], v[68:69] op_sel:[1,0]
	v_mov_b32_e32 v71, v69
	v_pk_add_f32 v[68:69], v[72:73], v[70:71]
	v_mul_f32_e32 v70, v49, v49
	v_pk_add_f32 v[68:69], v[68:69], v[68:69] op_sel:[0,1] op_sel_hi:[1,0]
	v_mov_b32_e32 v67, v65
	v_mov_b32_e32 v69, v70
	v_pk_add_f32 v[66:67], v[66:67], v[68:69]
	v_mul_f32_e32 v68, v53, v53
	v_mul_f32_e32 v71, v50, v50
	v_pk_fma_f32 v[68:69], v[52:53], v[52:53], v[68:69] op_sel_hi:[1,1,0]
	v_mul_f32_e32 v70, v55, v55
	v_mul_f32_e32 v72, v51, v51
	v_mov_b32_e32 v69, v71
	v_pk_fma_f32 v[70:71], v[54:55], v[54:55], v[70:71] op_sel_hi:[1,1,0]
	v_add_u32_e32 v64, 0x80, v166
	v_mov_b32_e32 v71, v72
	v_pk_add_f32 v[68:69], v[68:69], v[70:71]
	s_nop 0
	v_pk_add_f32 v[66:67], v[66:67], v[68:69]
	s_nop 0
	v_add_f32_e32 v65, v66, v67
	v_mov_b32_e32 v65, v234
	v_fmamk_f32 v65, v65, 0x3c800000, v182
	v_rsq_f32_e32 v65, v65
	s_nop 0
	v_mul_f32_e32 v66, v169, v65
	v_ashrrev_i32_e32 v65, 31, v64
	v_lshlrev_b64 v[68:69], 11, v[64:65]
	v_lshlrev_b64 v[64:65], 12, v[64:65]
	v_pk_mul_f32 v[56:57], v[56:57], v[66:67] op_sel_hi:[1,0]
	v_lshl_add_u64 v[64:65], s[14:15], 0, v[64:65]
	v_pk_mul_f32 v[70:71], v[136:137], v[56:57]
	v_pk_mul_f32 v[56:57], v[58:59], v[66:67] op_sel_hi:[1,0]
	v_lshl_add_u64 v[68:69], s[18:19], 0, v[68:69]
	v_pk_mul_f32 v[72:73], v[138:139], v[56:57]
	v_lshl_add_u64 v[56:57], v[64:65], 0, s[46:47]
	v_pk_mul_f32 v[60:61], v[60:61], v[66:67] op_sel_hi:[1,0]
	v_pk_mul_f32 v[62:63], v[62:63], v[66:67] op_sel_hi:[1,0]
	v_cndmask_b32_e32 v57, v69, v57, vcc
	v_cndmask_b32_e32 v56, v68, v56, vcc
	v_pk_mul_f32 v[60:61], v[140:141], v[60:61]
	v_pk_mul_f32 v[62:63], v[142:143], v[62:63]
	v_lshl_add_u64 v[56:57], v[56:57], 0, s[8:9]
	v_lshl_add_u64 v[74:75], v[56:57], 0, v[152:153]
	v_cvt_pk_bf16_f32 v56, v60, v61
	v_cvt_pk_bf16_f32 v57, v62, v63
	v_cvt_pk_bf16_f32 v58, v70, v71
	v_cvt_pk_bf16_f32 v59, v72, v73
	v_pk_mul_f32 v[48:49], v[48:49], v[66:67] op_sel_hi:[1,0]
	global_store_dwordx4 v[74:75], v[56:59], off
	v_pk_mul_f32 v[52:53], v[52:53], v[66:67] op_sel_hi:[1,0]
	v_pk_mul_f32 v[54:55], v[54:55], v[66:67] op_sel_hi:[1,0]
	v_pk_mul_f32 v[56:57], v[128:129], v[48:49]
	v_pk_mul_f32 v[48:49], v[50:51], v[66:67] op_sel_hi:[1,0]
	v_pk_mul_f32 v[52:53], v[132:133], v[52:53]
	v_pk_mul_f32 v[58:59], v[130:131], v[48:49]
	v_cndmask_b32_e32 v49, v69, v65, vcc
	v_cndmask_b32_e32 v48, v68, v64, vcc
	v_lshl_add_u64 v[48:49], v[48:49], 0, s[8:9]
	v_pk_mul_f32 v[54:55], v[134:135], v[54:55]
	v_lshl_add_u64 v[48:49], v[48:49], 0, s[0:1]
	v_lshl_add_u64 v[60:61], v[48:49], 0, v[152:153]
	v_cvt_pk_bf16_f32 v48, v52, v53
; __device__ __forceinline__ u32x4 pack8_bf16(const float (&o)[8]) { u32x4 w; w.x = cvt_pk_bf16(o[0], o[1]); w.y = cvt_pk_bf16(o[2], o[3]); w.z = cvt_pk_bf16(o[4], o[5]); w.w = cvt_pk_bf16(o[6], o[7]); return w; }
;     __device__ __forceinline__ void operator()(const f32x4 (&acc)[2][2][4][2], const Unit& u, int wr, int wc, int fr, int fq) const {
;     ...
;                         for (int n = 0; n < 2; ++n) { const f32x4 x = acc[ai][bj][m][n]; ss += (x[0] * x[0] + x[1] * x[1]) + (x[2] * x[2] + x[3] * x[3]); }
;                     ss += __shfl_xor(ss, 16); ss += __shfl_xor(ss, 32);
;                     const float rstd = __builtin_amdgcn_rsqf(ss * (1.0f / 64.0f) + 1e-6f) * sc;
;                     const size_t row = (size_t)(row0 + ai * HALF + m * 16);
; #pragma unroll
;                     for (int bj = 0; bj < 2; ++bj) { float o[8];
; #pragma unroll
;                         for (int k = 0; k < 8; ++k) o[k] = acc[ai][bj][m][k >> 2][k & 3] * rstd * gn[bj][k];
;                         bf16_t* dst = (sec == 4) ? (QS + row * 2048 + 1024 + head * 64 + 32 * bj + 8 * fq) : (SK + row * 1024 + head * 64 + 32 * bj + 8 * fq);
;                         *(u32x4*)dst = pack8_bf16(o); }
;                 }
	v_cvt_pk_bf16_f32 v49, v54, v55
	v_cvt_pk_bf16_f32 v50, v56, v57
	v_cvt_pk_bf16_f32 v51, v58, v59
	global_store_dwordx4 v[60:61], v[48:51], off
	s_nop 1
	v_pk_mul_f32 v[48:49], v[46:47], v[46:47]
	v_pk_mul_f32 v[50:51], v[44:45], v[44:45]
	s_nop 0
	v_pk_mov_b32 v[52:53], v[50:51], v[48:49] op_sel:[1,0]
	v_mov_b32_e32 v51, v49
	v_pk_add_f32 v[48:49], v[52:53], v[50:51]
	v_pk_mul_f32 v[50:51], v[42:43], v[42:43]
	v_pk_mul_f32 v[52:53], v[40:41], v[40:41]
	v_pk_add_f32 v[48:49], v[48:49], v[48:49] op_sel:[0,1] op_sel_hi:[1,0]
	v_pk_mov_b32 v[54:55], v[52:53], v[50:51] op_sel:[1,0]
	v_mov_b32_e32 v53, v51
	v_pk_add_f32 v[50:51], v[54:55], v[52:53]
	v_mul_f32_e32 v52, v32, v32
	v_mul_f32_e32 v53, v33, v33
	v_pk_add_f32 v[50:51], v[50:51], v[50:51] op_sel:[0,1] op_sel_hi:[1,0]
	v_mov_b32_e32 v49, v52
	v_mov_b32_e32 v51, v53
	v_pk_add_f32 v[48:49], v[48:49], v[50:51]
	v_mul_f32_e32 v50, v37, v37
	v_mul_f32_e32 v52, v39, v39
	v_mul_f32_e32 v54, v34, v34
	v_mul_f32_e32 v55, v35, v35
	v_pk_fma_f32 v[50:51], v[36:37], v[36:37], v[50:51] op_sel_hi:[1,1,0]
	v_pk_fma_f32 v[52:53], v[38:39], v[38:39], v[52:53] op_sel_hi:[1,1,0]
	v_mov_b32_e32 v51, v54
	v_mov_b32_e32 v53, v55
	v_pk_add_f32 v[50:51], v[50:51], v[52:53]
	s_nop 0
	v_pk_add_f32 v[48:49], v[48:49], v[50:51]
	v_add_u32_e32 v50, 0x90, v166
	v_add_f32_e32 v48, v48, v49
	v_ashrrev_i32_e32 v51, 31, v50
	v_lshlrev_b64 v[52:53], 11, v[50:51]
	v_lshlrev_b64 v[50:51], 12, v[50:51]
	v_lshl_add_u64 v[50:51], s[14:15], 0, v[50:51]
	v_lshl_add_u64 v[52:53], s[18:19], 0, v[52:53]
	v_mov_b32_e32 v48, v235
	v_fmamk_f32 v48, v48, 0x3c800000, v182
	v_rsq_f32_e32 v48, v48
	s_nop 0
	v_mul_f32_e32 v48, v169, v48
	v_pk_mul_f32 v[40:41], v[40:41], v[48:49] op_sel_hi:[1,0]
	v_pk_mul_f32 v[44:45], v[44:45], v[48:49] op_sel_hi:[1,0]
	v_pk_mul_f32 v[54:55], v[136:137], v[40:41]
	v_pk_mul_f32 v[40:41], v[42:43], v[48:49] op_sel_hi:[1,0]
	v_pk_mul_f32 v[46:47], v[46:47], v[48:49] op_sel_hi:[1,0]
	v_pk_mul_f32 v[56:57], v[138:139], v[40:41]
	v_lshl_add_u64 v[40:41], v[50:51], 0, s[46:47]
	v_cndmask_b32_e32 v41, v53, v41, vcc
	v_cndmask_b32_e32 v40, v52, v40, vcc
	v_pk_mul_f32 v[44:45], v[140:141], v[44:45]
	v_pk_mul_f32 v[46:47], v[142:143], v[46:47]
	v_lshl_add_u64 v[40:41], v[40:41], 0, s[8:9]
	v_lshl_add_u64 v[58:59], v[40:41], 0, v[152:153]
	v_cvt_pk_bf16_f32 v40, v44, v45
	v_cvt_pk_bf16_f32 v41, v46, v47
	v_cvt_pk_bf16_f32 v42, v54, v55
	v_cvt_pk_bf16_f32 v43, v56, v57
	v_pk_mul_f32 v[32:33], v[32:33], v[48:49] op_sel_hi:[1,0]
	global_store_dwordx4 v[58:59], v[40:43], off
	v_pk_mul_f32 v[36:37], v[36:37], v[48:49] op_sel_hi:[1,0]
	v_pk_mul_f32 v[38:39], v[38:39], v[48:49] op_sel_hi:[1,0]
	v_pk_mul_f32 v[40:41], v[128:129], v[32:33]
	v_pk_mul_f32 v[32:33], v[34:35], v[48:49] op_sel_hi:[1,0]
	v_pk_mul_f32 v[36:37], v[132:133], v[36:37]
	v_pk_mul_f32 v[42:43], v[130:131], v[32:33]
	v_cndmask_b32_e32 v33, v53, v51, vcc
	v_cndmask_b32_e32 v32, v52, v50, vcc
	v_lshl_add_u64 v[32:33], v[32:33], 0, s[8:9]
	v_pk_mul_f32 v[38:39], v[134:135], v[38:39]
	v_lshl_add_u64 v[32:33], v[32:33], 0, s[0:1]
	v_lshl_add_u64 v[44:45], v[32:33], 0, v[152:153]
	v_cvt_pk_bf16_f32 v32, v36, v37
	v_cvt_pk_bf16_f32 v33, v38, v39
	v_cvt_pk_bf16_f32 v34, v40, v41
	v_cvt_pk_bf16_f32 v35, v42, v43
	global_store_dwordx4 v[44:45], v[32:35], off
	s_nop 1
	v_pk_mul_f32 v[32:33], v[30:31], v[30:31]
	v_pk_mul_f32 v[34:35], v[28:29], v[28:29]
	s_nop 0
	v_pk_mov_b32 v[36:37], v[34:35], v[32:33] op_sel:[1,0]
	v_mov_b32_e32 v35, v33
	v_pk_add_f32 v[32:33], v[36:37], v[34:35]
	v_pk_mul_f32 v[34:35], v[26:27], v[26:27]
	v_pk_mul_f32 v[36:37], v[24:25], v[24:25]
	v_pk_add_f32 v[32:33], v[32:33], v[32:33] op_sel:[0,1] op_sel_hi:[1,0]
	v_pk_mov_b32 v[38:39], v[36:37], v[34:35] op_sel:[1,0]
	v_mov_b32_e32 v37, v35
	v_pk_add_f32 v[34:35], v[38:39], v[36:37]
	v_mul_f32_e32 v36, v16, v16
	v_mul_f32_e32 v37, v17, v17
	v_pk_add_f32 v[34:35], v[34:35], v[34:35] op_sel:[0,1] op_sel_hi:[1,0]
	v_mov_b32_e32 v33, v36
	v_mov_b32_e32 v35, v37
	v_pk_add_f32 v[32:33], v[32:33], v[34:35]
	v_mul_f32_e32 v34, v21, v21
	v_mul_f32_e32 v36, v23, v23
	v_mul_f32_e32 v38, v18, v18
	v_mul_f32_e32 v39, v19, v19
	v_pk_fma_f32 v[34:35], v[20:21], v[20:21], v[34:35] op_sel_hi:[1,1,0]
	v_pk_fma_f32 v[36:37], v[22:23], v[22:23], v[36:37] op_sel_hi:[1,1,0]
	v_mov_b32_e32 v35, v38
	v_mov_b32_e32 v37, v39
	v_pk_add_f32 v[34:35], v[34:35], v[36:37]
	s_nop 0
	v_pk_add_f32 v[32:33], v[32:33], v[34:35]
	v_add_u32_e32 v34, 0xa0, v166
	v_add_f32_e32 v32, v32, v33
	v_ashrrev_i32_e32 v35, 31, v34
	v_lshlrev_b64 v[36:37], 11, v[34:35]
	v_lshlrev_b64 v[34:35], 12, v[34:35]
	v_lshl_add_u64 v[34:35], s[14:15], 0, v[34:35]
	v_lshl_add_u64 v[36:37], s[18:19], 0, v[36:37]
	v_mov_b32_e32 v32, v236
	v_fmamk_f32 v32, v32, 0x3c800000, v182
	v_rsq_f32_e32 v32, v32
	s_nop 0
; __device__ __forceinline__ u32x4 pack8_bf16(const float (&o)[8]) { u32x4 w; w.x = cvt_pk_bf16(o[0], o[1]); w.y = cvt_pk_bf16(o[2], o[3]); w.z = cvt_pk_bf16(o[4], o[5]); w.w = cvt_pk_bf16(o[6], o[7]); return w; }
;     __device__ __forceinline__ void operator()(const f32x4 (&acc)[2][2][4][2], const Unit& u, int wr, int wc, int fr, int fq) const {
;     ...
;                         for (int n = 0; n < 2; ++n) { const f32x4 x = acc[ai][bj][m][n]; ss += (x[0] * x[0] + x[1] * x[1]) + (x[2] * x[2] + x[3] * x[3]); }
;                     ss += __shfl_xor(ss, 16); ss += __shfl_xor(ss, 32);
;                     const float rstd = __builtin_amdgcn_rsqf(ss * (1.0f / 64.0f) + 1e-6f) * sc;
;                     const size_t row = (size_t)(row0 + ai * HALF + m * 16);
; #pragma unroll
;                     for (int bj = 0; bj < 2; ++bj) { float o[8];
; #pragma unroll
;                         for (int k = 0; k < 8; ++k) o[k] = acc[ai][bj][m][k >> 2][k & 3] * rstd * gn[bj][k];
;                         bf16_t* dst = (sec == 4) ? (QS + row * 2048 + 1024 + head * 64 + 32 * bj + 8 * fq) : (SK + row * 1024 + head * 64 + 32 * bj + 8 * fq);
;                         *(u32x4*)dst = pack8_bf16(o); }
;                 }
	v_mul_f32_e32 v32, v169, v32
	v_pk_mul_f32 v[24:25], v[24:25], v[32:33] op_sel_hi:[1,0]
	v_pk_mul_f32 v[28:29], v[28:29], v[32:33] op_sel_hi:[1,0]
	v_pk_mul_f32 v[38:39], v[136:137], v[24:25]
	v_pk_mul_f32 v[24:25], v[26:27], v[32:33] op_sel_hi:[1,0]
	v_pk_mul_f32 v[30:31], v[30:31], v[32:33] op_sel_hi:[1,0]
	v_pk_mul_f32 v[40:41], v[138:139], v[24:25]
	v_lshl_add_u64 v[24:25], v[34:35], 0, s[46:47]
	v_cndmask_b32_e32 v25, v37, v25, vcc
	v_cndmask_b32_e32 v24, v36, v24, vcc
	v_pk_mul_f32 v[28:29], v[140:141], v[28:29]
	v_pk_mul_f32 v[30:31], v[142:143], v[30:31]
	v_lshl_add_u64 v[24:25], v[24:25], 0, s[8:9]
	v_lshl_add_u64 v[42:43], v[24:25], 0, v[152:153]
	v_cvt_pk_bf16_f32 v24, v28, v29
	v_cvt_pk_bf16_f32 v25, v30, v31
	v_cvt_pk_bf16_f32 v26, v38, v39
	v_cvt_pk_bf16_f32 v27, v40, v41
	v_pk_mul_f32 v[16:17], v[16:17], v[32:33] op_sel_hi:[1,0]
	global_store_dwordx4 v[42:43], v[24:27], off
	v_pk_mul_f32 v[20:21], v[20:21], v[32:33] op_sel_hi:[1,0]
	v_pk_mul_f32 v[22:23], v[22:23], v[32:33] op_sel_hi:[1,0]
	v_pk_mul_f32 v[24:25], v[128:129], v[16:17]
	v_pk_mul_f32 v[16:17], v[18:19], v[32:33] op_sel_hi:[1,0]
	v_pk_mul_f32 v[20:21], v[132:133], v[20:21]
	v_pk_mul_f32 v[26:27], v[130:131], v[16:17]
	v_cndmask_b32_e32 v17, v37, v35, vcc
	v_cndmask_b32_e32 v16, v36, v34, vcc
	v_lshl_add_u64 v[16:17], v[16:17], 0, s[8:9]
	v_pk_mul_f32 v[22:23], v[134:135], v[22:23]
	v_lshl_add_u64 v[16:17], v[16:17], 0, s[0:1]
	v_lshl_add_u64 v[28:29], v[16:17], 0, v[152:153]
	v_cvt_pk_bf16_f32 v16, v20, v21
	v_cvt_pk_bf16_f32 v17, v22, v23
	v_cvt_pk_bf16_f32 v18, v24, v25
	v_cvt_pk_bf16_f32 v19, v26, v27
	global_store_dwordx4 v[28:29], v[16:19], off
	s_nop 1
	v_pk_mul_f32 v[16:17], v[14:15], v[14:15]
	v_pk_mul_f32 v[18:19], v[12:13], v[12:13]
	s_nop 0
	v_pk_mov_b32 v[20:21], v[18:19], v[16:17] op_sel:[1,0]
	v_mov_b32_e32 v19, v17
	v_pk_add_f32 v[16:17], v[20:21], v[18:19]
	v_pk_mul_f32 v[18:19], v[10:11], v[10:11]
	v_pk_mul_f32 v[20:21], v[8:9], v[8:9]
	v_pk_add_f32 v[16:17], v[16:17], v[16:17] op_sel:[0,1] op_sel_hi:[1,0]
	v_pk_mov_b32 v[22:23], v[20:21], v[18:19] op_sel:[1,0]
	v_mov_b32_e32 v21, v19
	v_pk_add_f32 v[18:19], v[22:23], v[20:21]
	v_mul_f32_e32 v20, v0, v0
	v_mul_f32_e32 v21, v1, v1
	v_pk_add_f32 v[18:19], v[18:19], v[18:19] op_sel:[0,1] op_sel_hi:[1,0]
	v_mov_b32_e32 v17, v20
	v_mov_b32_e32 v19, v21
	v_pk_add_f32 v[16:17], v[16:17], v[18:19]
	v_mul_f32_e32 v18, v5, v5
	v_mul_f32_e32 v20, v7, v7
	v_mul_f32_e32 v22, v2, v2
	v_mul_f32_e32 v23, v3, v3
	v_pk_fma_f32 v[18:19], v[4:5], v[4:5], v[18:19] op_sel_hi:[1,1,0]
	v_pk_fma_f32 v[20:21], v[6:7], v[6:7], v[20:21] op_sel_hi:[1,1,0]
	v_mov_b32_e32 v19, v22
	v_mov_b32_e32 v21, v23
	v_pk_add_f32 v[18:19], v[18:19], v[20:21]
	s_nop 0
	v_pk_add_f32 v[16:17], v[16:17], v[18:19]
	v_add_u32_e32 v18, 0xb0, v166
	v_add_f32_e32 v16, v16, v17
	v_ashrrev_i32_e32 v19, 31, v18
	v_lshlrev_b64 v[20:21], 11, v[18:19]
	v_lshlrev_b64 v[18:19], 12, v[18:19]
	v_lshl_add_u64 v[18:19], s[14:15], 0, v[18:19]
	v_lshl_add_u64 v[20:21], s[18:19], 0, v[20:21]
	v_mov_b32_e32 v16, v237
	v_fmamk_f32 v16, v16, 0x3c800000, v182
	v_rsq_f32_e32 v16, v16
	s_nop 0
	v_mul_f32_e32 v16, v169, v16
	v_pk_mul_f32 v[8:9], v[8:9], v[16:17] op_sel_hi:[1,0]
	v_pk_mul_f32 v[12:13], v[12:13], v[16:17] op_sel_hi:[1,0]
	v_pk_mul_f32 v[22:23], v[136:137], v[8:9]
	v_pk_mul_f32 v[8:9], v[10:11], v[16:17] op_sel_hi:[1,0]
	v_pk_mul_f32 v[14:15], v[14:15], v[16:17] op_sel_hi:[1,0]
	v_pk_mul_f32 v[24:25], v[138:139], v[8:9]
	v_lshl_add_u64 v[8:9], v[18:19], 0, s[46:47]
	v_cndmask_b32_e32 v9, v21, v9, vcc
	v_cndmask_b32_e32 v8, v20, v8, vcc
	v_pk_mul_f32 v[12:13], v[140:141], v[12:13]
	v_pk_mul_f32 v[14:15], v[142:143], v[14:15]
	v_lshl_add_u64 v[8:9], v[8:9], 0, s[8:9]
	v_lshl_add_u64 v[26:27], v[8:9], 0, v[152:153]
	v_cvt_pk_bf16_f32 v8, v12, v13
	v_cvt_pk_bf16_f32 v9, v14, v15
	v_cvt_pk_bf16_f32 v10, v22, v23
	v_cvt_pk_bf16_f32 v11, v24, v25
	v_pk_mul_f32 v[0:1], v[0:1], v[16:17] op_sel_hi:[1,0]
	global_store_dwordx4 v[26:27], v[8:11], off
	v_pk_mul_f32 v[4:5], v[4:5], v[16:17] op_sel_hi:[1,0]
	v_pk_mul_f32 v[6:7], v[6:7], v[16:17] op_sel_hi:[1,0]
	v_pk_mul_f32 v[8:9], v[128:129], v[0:1]
	v_pk_mul_f32 v[0:1], v[2:3], v[16:17] op_sel_hi:[1,0]
	v_pk_mul_f32 v[4:5], v[132:133], v[4:5]
	v_pk_mul_f32 v[10:11], v[130:131], v[0:1]
	v_cndmask_b32_e32 v1, v21, v19, vcc
	v_cndmask_b32_e32 v0, v20, v18, vcc
	v_lshl_add_u64 v[0:1], v[0:1], 0, s[8:9]
	v_pk_mul_f32 v[6:7], v[134:135], v[6:7]
	v_lshl_add_u64 v[0:1], v[0:1], 0, s[0:1]
	v_lshl_add_u64 v[12:13], v[0:1], 0, v[152:153]
	v_cvt_pk_bf16_f32 v0, v4, v5
	v_cvt_pk_bf16_f32 v1, v6, v7
	v_cvt_pk_bf16_f32 v2, v8, v9
	v_cvt_pk_bf16_f32 v3, v10, v11
	global_store_dwordx4 v[12:13], v[0:3], off
	s_andn2_b64 vcc, exec, s[2:3]
	s_mov_b64 s[0:1], -1
	s_cbranch_vccnz .LBB0_92
